# attention tile loops: half-wave running-max exchange via v_permlane32_swap instead of ds_bpermute (no LDS round trip)
# speedup vs baseline: 1.0006x; 1.0006x over previous
; DI f32x16 mfma32(bf16x8 a, bf16x8 b, f32x16 c) { return __builtin_amdgcn_mfma_f32_32x32x16_bf16(a, b, c, 0, 0, 0); }
; DI int crow(int reg, int h) { return (reg & 3) + 8 * (reg >> 2) + 4 * h; }
; template <int DQK, int DV, int KW0, int MODE> ...
;     ...
;     {
;       bf16x8 kfa[DQK / 16], kfb[DQK / 16], qv[DQK / 16];
; #pragma unroll
;       for (int kk = 0; kk < DQK / 16; ++kk) {
;         kfa[kk] = *(const bf16x8*)(cur + r * (KS * 2) + kk * 32 + h * 16);
;         kfb[kk] = *(const bf16x8*)(cur + (32 + r) * (KS * 2) + kk * 32 + h * 16);
;         qv[kk] = QLDS ? *(const bf16x8*)(qbase + kk * 1024) : qf[kk];
;       }
; #pragma unroll
;       for (int kk = 0; kk < DQK / 16; ++kk) {
;         S0 = mfma32(kfa[kk], qv[kk], S0);
;         S1 = mfma32(kfb[kk], qv[kk], S1);
;       }
;       __builtin_amdgcn_sched_group_barrier(0x100, (QLDS ? 3 : 2) * (DQK / 16), 0);
;       __builtin_amdgcn_sched_group_barrier(0x008, 2 * (DQK / 16), 0);
;     }
;     if (MODE == 2) {
;       if (it >= 4) {
;         const int w = wlo + it - 4;
;         if (w < 2 || w > 3) {
;           const int kpos0 = (qn - 1) * 128 + 64 * w, qpos = qn * 128 + wid * 32 + r;
; #pragma unroll
;           for (int e = 0; e < 16; ++e) {
;             const int d0 = qpos - (kpos0 + crow(e, h)), d1 = d0 - 32;
;             if (d0 > 128 || d0 < -128) S0[e] = -1e30f;
;             if (d1 > 128 || d1 < -128) S1[e] = -1e30f;
;           }
;         }
;       }
;     }
;     float mx = S0[0];
; #pragma unroll
;     for (int e = 1; e < 16; ++e) mx = fmaxf(mx, S0[e]);
; #pragma unroll
;     for (int e = 0; e < 16; ++e) mx = fmaxf(mx, S1[e]);
;     mx = fmaxf(mx, __shfl_xor(mx, 32));
;     const float mn = fmaxf(m, mx);
;     const bool grow = __builtin_amdgcn_ballot_w64(mx > m) != 0ull;
;     const float alpha = __builtin_amdgcn_exp2f((m - mn) * c);
;     m = mn;
;     const float mc = mn * c;
;     float ps = 0.f;
; #pragma unroll
;     for (int e = 0; e < 16; ++e) { S0[e] = __builtin_amdgcn_exp2f(S0[e] * c - mc); ps += S0[e]; }
; #pragma unroll
;     for (int e = 0; e < 16; ++e) { S1[e] = __builtin_amdgcn_exp2f(S1[e] * c - mc); ps += S1[e]; }
;     if (grow) {
;       l *= alpha;
; #pragma unroll
;       for (int t = 0; t < DV / 32; ++t)
; #pragma unroll
;         for (int e = 0; e < 16; ++e) O[t][e] *= alpha;
;     }
.LBB0_41:
	s_bitcmp1_b32 s41, 0
	s_cselect_b32 s10, 0x7400, 0
	s_add_i32 s47, s10, 16
	v_add3_u32 v0, s47, v176, v177
	ds_read_b128 v[10:13], v0
	ds_read_b128 v[6:9], v182 offset:59392
	ds_read_b128 v[192:195], v0 offset:32
	ds_read_b128 v[2:5], v0 offset:4608
	ds_read_b128 v[218:221], v0 offset:4640
	ds_read_b128 v[222:225], v182 offset:60416
	ds_read_b128 v[226:229], v0 offset:64
	ds_read_b128 v[230:233], v0 offset:4672
	ds_read_b128 v[234:237], v182 offset:61440
	ds_read_b128 v[238:241], v0 offset:96
	ds_read_b128 v[242:245], v0 offset:4704
	ds_read_b128 v[246:249], v182 offset:62464
	s_setprio 1
	s_waitcnt lgkmcnt(10)
	v_mfma_f32_32x32x16_bf16 v[96:111], v[10:13], v[6:9], 0
	s_waitcnt lgkmcnt(6)
	v_mfma_f32_32x32x16_bf16 v[96:111], v[192:195], v[222:225], v[96:111]
	v_mfma_f32_32x32x16_bf16 v[80:95], v[2:5], v[6:9], 0
	v_max_f32_e32 v3, v183, v183
	s_waitcnt lgkmcnt(3)
	v_mfma_f32_32x32x16_bf16 v[96:111], v[226:229], v[234:237], v[96:111]
	v_mfma_f32_32x32x16_bf16 v[80:95], v[218:221], v[222:225], v[80:95]
	s_waitcnt lgkmcnt(0)
	v_mfma_f32_32x32x16_bf16 v[96:111], v[238:241], v[246:249], v[96:111]
	v_mfma_f32_32x32x16_bf16 v[80:95], v[230:233], v[234:237], v[80:95]
	s_nop 10
	v_max_f32_e32 v0, v97, v97
	v_max_f32_e32 v2, v96, v96
	v_max_f32_e32 v0, v2, v0
	v_max3_f32 v0, v0, v98, v99
	v_max3_f32 v0, v0, v100, v101
	v_max3_f32 v0, v0, v102, v103
	v_max3_f32 v0, v0, v104, v105
	v_mfma_f32_32x32x16_bf16 v[80:95], v[242:245], v[246:249], v[80:95]
	s_setprio 0
	v_max3_f32 v0, v0, v106, v107
	v_max3_f32 v0, v0, v108, v109
	v_max3_f32 v0, v0, v110, v111
	s_nop 8
	v_max3_f32 v0, v0, v80, v81
	v_max3_f32 v0, v0, v82, v83
	v_max3_f32 v0, v0, v84, v85
	v_max3_f32 v0, v0, v86, v87
	v_max3_f32 v0, v0, v88, v89
	v_max3_f32 v0, v0, v90, v91
	v_max3_f32 v0, v0, v92, v93
	v_max3_f32 v0, v0, v94, v95
	v_mov_b32_e32 v2, v0
	s_nop 1
	v_permlane32_swap_b32_e32 v2, v0
	s_waitcnt lgkmcnt(0)
	v_max_f32_e32 v0, v0, v2
	v_max_f32_e32 v3, v3, v0
	v_cmp_gt_f32_e32 vcc, v0, v183
	s_cbranch_vccz .LBB0_43
	v_sub_f32_e32 v0, v183, v3
	v_mul_f32_e32 v0, 0x3e38aa3b, v0
	v_exp_f32_e32 v0, v0
	s_nop 0
	v_pk_mul_f32 v[78:79], v[0:1], v[78:79] op_sel_hi:[0,1]
	v_pk_mul_f32 v[76:77], v[0:1], v[76:77] op_sel_hi:[0,1]
	v_pk_mul_f32 v[74:75], v[0:1], v[74:75] op_sel_hi:[0,1]
	v_pk_mul_f32 v[72:73], v[0:1], v[72:73] op_sel_hi:[0,1]
	v_pk_mul_f32 v[70:71], v[0:1], v[70:71] op_sel_hi:[0,1]
	v_pk_mul_f32 v[68:69], v[0:1], v[68:69] op_sel_hi:[0,1]
	v_pk_mul_f32 v[66:67], v[0:1], v[66:67] op_sel_hi:[0,1]
	v_pk_mul_f32 v[64:65], v[0:1], v[64:65] op_sel_hi:[0,1]
	v_pk_mul_f32 v[62:63], v[0:1], v[62:63] op_sel_hi:[0,1]
	v_pk_mul_f32 v[60:61], v[0:1], v[60:61] op_sel_hi:[0,1]
	v_pk_mul_f32 v[58:59], v[0:1], v[58:59] op_sel_hi:[0,1]
	v_pk_mul_f32 v[56:57], v[0:1], v[56:57] op_sel_hi:[0,1]
	v_pk_mul_f32 v[54:55], v[0:1], v[54:55] op_sel_hi:[0,1]
	v_pk_mul_f32 v[52:53], v[0:1], v[52:53] op_sel_hi:[0,1]
	v_pk_mul_f32 v[50:51], v[0:1], v[50:51] op_sel_hi:[0,1]
	v_pk_mul_f32 v[48:49], v[0:1], v[48:49] op_sel_hi:[0,1]
	v_pk_mul_f32 v[46:47], v[0:1], v[46:47] op_sel_hi:[0,1]
	v_pk_mul_f32 v[44:45], v[0:1], v[44:45] op_sel_hi:[0,1]
	v_pk_mul_f32 v[42:43], v[0:1], v[42:43] op_sel_hi:[0,1]
	v_pk_mul_f32 v[40:41], v[0:1], v[40:41] op_sel_hi:[0,1]
	v_pk_mul_f32 v[38:39], v[0:1], v[38:39] op_sel_hi:[0,1]
	v_pk_mul_f32 v[36:37], v[0:1], v[36:37] op_sel_hi:[0,1]
	v_pk_mul_f32 v[34:35], v[0:1], v[34:35] op_sel_hi:[0,1]
	v_pk_mul_f32 v[32:33], v[0:1], v[32:33] op_sel_hi:[0,1]
	v_pk_mul_f32 v[30:31], v[0:1], v[30:31] op_sel_hi:[0,1]
	v_pk_mul_f32 v[28:29], v[0:1], v[28:29] op_sel_hi:[0,1]
	v_pk_mul_f32 v[26:27], v[0:1], v[26:27] op_sel_hi:[0,1]
	v_pk_mul_f32 v[24:25], v[0:1], v[24:25] op_sel_hi:[0,1]
	v_pk_mul_f32 v[22:23], v[0:1], v[22:23] op_sel_hi:[0,1]
	v_pk_mul_f32 v[20:21], v[0:1], v[20:21] op_sel_hi:[0,1]
	v_pk_mul_f32 v[18:19], v[0:1], v[18:19] op_sel_hi:[0,1]
	v_pk_mul_f32 v[16:17], v[0:1], v[16:17] op_sel_hi:[0,1]
	v_mul_f32_e32 v145, v145, v0

; DI f32x16 mfma32(bf16x8 a, bf16x8 b, f32x16 c) { return __builtin_amdgcn_mfma_f32_32x32x16_bf16(a, b, c, 0, 0, 0); }
; DI int crow(int reg, int h) { return (reg & 3) + 8 * (reg >> 2) + 4 * h; }
; template <int DQK, int DV, int KW0, int MODE> ...
;     ...
;     {
;       bf16x8 kfa[DQK / 16], kfb[DQK / 16], qv[DQK / 16];
; #pragma unroll
;       for (int kk = 0; kk < DQK / 16; ++kk) {
;         kfa[kk] = *(const bf16x8*)(cur + r * (KS * 2) + kk * 32 + h * 16);
;         kfb[kk] = *(const bf16x8*)(cur + (32 + r) * (KS * 2) + kk * 32 + h * 16);
;         qv[kk] = QLDS ? *(const bf16x8*)(qbase + kk * 1024) : qf[kk];
;       }
; #pragma unroll
;       for (int kk = 0; kk < DQK / 16; ++kk) {
;         S0 = mfma32(kfa[kk], qv[kk], S0);
;         S1 = mfma32(kfb[kk], qv[kk], S1);
;       }
;       __builtin_amdgcn_sched_group_barrier(0x100, (QLDS ? 3 : 2) * (DQK / 16), 0);
;       __builtin_amdgcn_sched_group_barrier(0x008, 2 * (DQK / 16), 0);
;     }
;     if (MODE == 2) {
;       if (it >= 4) {
;         const int w = wlo + it - 4;
;         if (w < 2 || w > 3) {
;           const int kpos0 = (qn - 1) * 128 + 64 * w, qpos = qn * 128 + wid * 32 + r;
; #pragma unroll
;           for (int e = 0; e < 16; ++e) {
;             const int d0 = qpos - (kpos0 + crow(e, h)), d1 = d0 - 32;
;             if (d0 > 128 || d0 < -128) S0[e] = -1e30f;
;             if (d1 > 128 || d1 < -128) S1[e] = -1e30f;
;           }
;         }
;       }
;     }
;     float mx = S0[0];
; #pragma unroll
;     for (int e = 1; e < 16; ++e) mx = fmaxf(mx, S0[e]);
; #pragma unroll
;     for (int e = 0; e < 16; ++e) mx = fmaxf(mx, S1[e]);
;     mx = fmaxf(mx, __shfl_xor(mx, 32));
;     const float mn = fmaxf(m, mx);
;     const bool grow = __builtin_amdgcn_ballot_w64(mx > m) != 0ull;
;     const float alpha = __builtin_amdgcn_exp2f((m - mn) * c);
;     m = mn;
;     const float mc = mn * c;
;     float ps = 0.f;
; #pragma unroll
;     for (int e = 0; e < 16; ++e) { S0[e] = __builtin_amdgcn_exp2f(S0[e] * c - mc); ps += S0[e]; }
; #pragma unroll
;     for (int e = 0; e < 16; ++e) { S1[e] = __builtin_amdgcn_exp2f(S1[e] * c - mc); ps += S1[e]; }
;     if (grow) {
;       l *= alpha;
; #pragma unroll
;       for (int t = 0; t < DV / 32; ++t)
; #pragma unroll
;         for (int e = 0; e < 16; ++e) O[t][e] *= alpha;
;     }
.LBB0_45:
	v_add3_u32 v0, s41, v176, v177
	ds_read_b128 v[12:15], v0
	ds_read_b128 v[8:11], v182 offset:59392
	ds_read_b128 v[192:195], v0 offset:32
	ds_read_b128 v[4:7], v0 offset:4608
	ds_read_b128 v[218:221], v0 offset:4640
	ds_read_b128 v[222:225], v182 offset:60416
	ds_read_b128 v[226:229], v0 offset:64
	ds_read_b128 v[230:233], v0 offset:4672
	ds_read_b128 v[234:237], v182 offset:61440
	ds_read_b128 v[238:241], v0 offset:96
	ds_read_b128 v[242:245], v0 offset:4704
	ds_read_b128 v[246:249], v182 offset:62464
	s_waitcnt lgkmcnt(10)
	v_mfma_f32_32x32x16_bf16 v[96:111], v[12:15], v[8:11], 0
	s_waitcnt lgkmcnt(6)
	v_mfma_f32_32x32x16_bf16 v[96:111], v[192:195], v[222:225], v[96:111]
	v_mfma_f32_32x32x16_bf16 v[80:95], v[4:7], v[8:11], 0
	v_max_f32_e32 v4, v3, v3
	s_waitcnt lgkmcnt(3)
	v_mfma_f32_32x32x16_bf16 v[96:111], v[226:229], v[234:237], v[96:111]
	v_mfma_f32_32x32x16_bf16 v[80:95], v[218:221], v[222:225], v[80:95]
	s_waitcnt lgkmcnt(0)
	v_mfma_f32_32x32x16_bf16 v[96:111], v[238:241], v[246:249], v[96:111]
	v_mfma_f32_32x32x16_bf16 v[80:95], v[230:233], v[234:237], v[80:95]
	s_nop 10
	v_max_f32_e32 v0, v97, v97
	v_max_f32_e32 v2, v96, v96
	v_max_f32_e32 v0, v2, v0
	v_max3_f32 v0, v0, v98, v99
	v_max3_f32 v0, v0, v100, v101
	v_max3_f32 v0, v0, v102, v103
	v_max3_f32 v0, v0, v104, v105
	v_mfma_f32_32x32x16_bf16 v[80:95], v[242:245], v[246:249], v[80:95]
	v_max3_f32 v0, v0, v106, v107
	v_max3_f32 v0, v0, v108, v109
	v_max3_f32 v0, v0, v110, v111
	s_nop 8
	v_max3_f32 v0, v0, v80, v81
	v_max3_f32 v0, v0, v82, v83
	v_max3_f32 v0, v0, v84, v85
	v_max3_f32 v0, v0, v86, v87
	v_max3_f32 v0, v0, v88, v89
	v_max3_f32 v0, v0, v90, v91
	v_max3_f32 v0, v0, v92, v93
	v_max3_f32 v0, v0, v94, v95
	v_mov_b32_e32 v2, v0
	s_nop 1
	v_permlane32_swap_b32_e32 v2, v0
	s_waitcnt lgkmcnt(0)
	v_max_f32_e32 v2, v0, v2
	v_max_f32_e32 v0, v4, v2
	v_cmp_gt_f32_e32 vcc, v2, v3
	s_cbranch_vccz .LBB0_47
	v_sub_f32_e32 v2, v3, v0
	v_mul_f32_e32 v2, 0x3e38aa3b, v2
	v_exp_f32_e32 v2, v2
	s_nop 0
	v_pk_mul_f32 v[78:79], v[2:3], v[78:79] op_sel_hi:[0,1]
	v_pk_mul_f32 v[76:77], v[2:3], v[76:77] op_sel_hi:[0,1]
	v_pk_mul_f32 v[74:75], v[2:3], v[74:75] op_sel_hi:[0,1]
	v_pk_mul_f32 v[72:73], v[2:3], v[72:73] op_sel_hi:[0,1]
	v_pk_mul_f32 v[70:71], v[2:3], v[70:71] op_sel_hi:[0,1]
	v_pk_mul_f32 v[68:69], v[2:3], v[68:69] op_sel_hi:[0,1]
	v_pk_mul_f32 v[66:67], v[2:3], v[66:67] op_sel_hi:[0,1]
	v_pk_mul_f32 v[64:65], v[2:3], v[64:65] op_sel_hi:[0,1]
	v_pk_mul_f32 v[62:63], v[2:3], v[62:63] op_sel_hi:[0,1]
	v_pk_mul_f32 v[60:61], v[2:3], v[60:61] op_sel_hi:[0,1]
	v_pk_mul_f32 v[58:59], v[2:3], v[58:59] op_sel_hi:[0,1]
	v_pk_mul_f32 v[56:57], v[2:3], v[56:57] op_sel_hi:[0,1]
	v_pk_mul_f32 v[54:55], v[2:3], v[54:55] op_sel_hi:[0,1]
	v_pk_mul_f32 v[52:53], v[2:3], v[52:53] op_sel_hi:[0,1]
	v_pk_mul_f32 v[50:51], v[2:3], v[50:51] op_sel_hi:[0,1]
	v_pk_mul_f32 v[48:49], v[2:3], v[48:49] op_sel_hi:[0,1]
	v_pk_mul_f32 v[46:47], v[2:3], v[46:47] op_sel_hi:[0,1]
	v_pk_mul_f32 v[44:45], v[2:3], v[44:45] op_sel_hi:[0,1]
	v_pk_mul_f32 v[42:43], v[2:3], v[42:43] op_sel_hi:[0,1]
	v_pk_mul_f32 v[40:41], v[2:3], v[40:41] op_sel_hi:[0,1]
	v_pk_mul_f32 v[38:39], v[2:3], v[38:39] op_sel_hi:[0,1]
	v_pk_mul_f32 v[36:37], v[2:3], v[36:37] op_sel_hi:[0,1]
	v_pk_mul_f32 v[34:35], v[2:3], v[34:35] op_sel_hi:[0,1]
	v_pk_mul_f32 v[32:33], v[2:3], v[32:33] op_sel_hi:[0,1]
	v_pk_mul_f32 v[30:31], v[2:3], v[30:31] op_sel_hi:[0,1]
	v_pk_mul_f32 v[28:29], v[2:3], v[28:29] op_sel_hi:[0,1]
	v_pk_mul_f32 v[26:27], v[2:3], v[26:27] op_sel_hi:[0,1]
	v_pk_mul_f32 v[24:25], v[2:3], v[24:25] op_sel_hi:[0,1]
	v_pk_mul_f32 v[22:23], v[2:3], v[22:23] op_sel_hi:[0,1]
	v_pk_mul_f32 v[20:21], v[2:3], v[20:21] op_sel_hi:[0,1]
	v_pk_mul_f32 v[18:19], v[2:3], v[18:19] op_sel_hi:[0,1]
	v_pk_mul_f32 v[16:17], v[2:3], v[16:17] op_sel_hi:[0,1]
	v_mul_f32_e32 v145, v145, v2

; template <int DQK, int DV, int KW0, int WHICH> ...
;   constexpr int KCH = DQK / 8, NKC = (64 * KCH) / 256, VCH = DV / 8, NVU = (32 * VCH) / 256;
;   if (WHICH & 1)
; #pragma unroll
;   for (int i = 0; i < NKC; ++i) {
;     const int id = tid + 256 * i, key = id / KCH, ch = id % KCH;
;     const bf16_t* src;
;     if constexpr (KW0 == DQK) src = (const bf16_t*)((const char*)(k0p + (size_t)krow * ldk0) + (unsigned)((key * ldk0 + ch * 8) * 2));
;     else src = (ch * 8 < KW0) ? (k0p + (size_t)(krow + key) * ldk0 + ch * 8) : (k1p + (size_t)(krow + key) * ldk1 + (ch * 8 - KW0));
;     kreg[i] = *(const GAS u32x4*)src;
;   }
;   if (WHICH & 2)
; #pragma unroll
;   for (int u = 0; u < NVU; ++u) {
;     const int id = tid + 256 * u, kp = id / VCH, ch = id % VCH;
;     const char* vb = (const char*)(vp + (size_t)krow * ldv);
;     vreg[u][0] = *(const GAS u32x4*)(vb + (unsigned)((2 * kp * ldv + ch * 8) * 2));
;     vreg[u][1] = *(const GAS u32x4*)(vb + (unsigned)(((2 * kp + 1) * ldv + ch * 8) * 2));
;   }
; }
; template <int DQK, int DV>
; DI void attn_sstore(const u32x4 (&kreg)[(64 * (DQK / 8)) / 256], const u32x4 (&vreg)[(32 * (DV / 8)) / 256][2], char* stage, int tid) {
;   constexpr int KCH = DQK / 8, NKC = (64 * KCH) / 256, VCH = DV / 8, NVU = (32 * VCH) / 256, KS = DQK + 8, KB = 64 * KS * 2, VSB = DV * 2 + 64;
; #pragma unroll
;   for (int i = 0; i < NKC; ++i) {
;     const int id = tid + 256 * i, key = id / KCH, ch = id % KCH;
;     *(u32x4*)(stage + key * (KS * 2) + ch * 16) = kreg[i];
;   }
; #pragma unroll
;   for (int u = 0; u < NVU; ++u) {
;     const int id = tid + 256 * u, kp = id / VCH, ch = id % VCH;
;     *(u32x4*)(stage + KB + (2 * kp) * VSB + ch * 16) = vreg[u][0];
;     *(u32x4*)(stage + KB + (2 * kp + 1) * VSB + ch * 16) = vreg[u][1];
;   }
; template <int DQK, int DV, int KW0, int MODE> ...
;     ...
;   for (int it = 0; it < nkt; ++it) {
;     const char* cur = smem + (it & 1) * STG;
;     const bool more = (it + 1 < nkt);
;     if (DV <= 64) { if (more) attn_gload<DQK, DV, KW0, 3>(kreg, vreg, k0p, ldk0, k1p, ldk1, vp, ldv, key_tile_row<MODE>(it + 1, b, qn, wlo), tid); __builtin_amdgcn_sched_barrier(0); }
;     f32x16 S0, S1;
; #pragma unroll
;     for (int e = 0; e < 16; ++e) { S0[e] = 0.f; S1[e] = 0.f; }
;     {
;       bf16x8 kfa[DQK / 16], kfb[DQK / 16], qv[DQK / 16];
; #pragma unroll
;       for (int kk = 0; kk < DQK / 16; ++kk) {
.LBB0_67:
	s_lshl_b32 s10, s23, 8
	s_add_u32 s12, s20, s10
	s_addc_u32 s13, s21, 0
	s_lshl_b32 s19, s18, 8
	s_add_i32 s14, s19, 0x10000
	v_add_u32_e32 v28, s14, v152
	v_ashrrev_i32_e32 v29, 31, v28
	s_barrier
	s_and_saveexec_b64 s[16:17], s[40:41]
	s_xor_b64 s[16:17], exec, s[16:17]
	s_movk_i32 s10, 0xff80
	v_mad_i64_i32 v[26:27], s[46:47], v28, s35, v[116:117]
	s_mov_b32 s11, -1
	v_lshl_add_u64 v[26:27], v[26:27], 0, s[10:11]
	s_andn2_saveexec_b64 s[16:17], s[16:17]
	v_lshlrev_b64 v[26:27], 11, v[28:29]
	v_lshl_add_u64 v[26:27], s[12:13], 0, v[26:27]
	v_lshl_add_u64 v[26:27], v[118:119], 1, v[26:27]
	s_or_b64 exec, exec, s[16:17]
	global_load_dwordx4 v[26:29], v[26:27], off
	v_add_u32_e32 v32, s14, v153
	v_ashrrev_i32_e32 v33, 31, v32
	s_and_saveexec_b64 s[16:17], s[42:43]
	s_xor_b64 s[16:17], exec, s[16:17]
	s_movk_i32 s10, 0xff80
	v_mad_i64_i32 v[30:31], s[46:47], v32, s35, v[120:121]
	s_mov_b32 s11, -1
	v_lshl_add_u64 v[30:31], v[30:31], 0, s[10:11]
	s_andn2_saveexec_b64 s[16:17], s[16:17]
	v_lshlrev_b64 v[30:31], 11, v[32:33]
	v_lshl_add_u64 v[30:31], s[12:13], 0, v[30:31]
	v_lshl_add_u64 v[30:31], v[122:123], 1, v[30:31]
	s_or_b64 exec, exec, s[16:17]
	global_load_dwordx4 v[30:33], v[30:31], off
	v_add_u32_e32 v38, s14, v154
	v_ashrrev_i32_e32 v39, 31, v38
	s_and_saveexec_b64 s[16:17], s[44:45]
	s_xor_b64 s[16:17], exec, s[16:17]
	s_movk_i32 s10, 0xff80
	v_mad_i64_i32 v[34:35], s[46:47], v38, s35, v[126:127]
	s_mov_b32 s11, -1
	v_lshl_add_u64 v[36:37], v[34:35], 0, s[10:11]
	s_or_saveexec_b64 s[16:17], s[16:17]
	v_mov_b64_e32 v[34:35], v[124:125]
	s_xor_b64 exec, exec, s[16:17]
	v_lshlrev_b64 v[34:35], 11, v[38:39]
	v_lshl_add_u64 v[34:35], s[12:13], 0, v[34:35]
	v_lshl_add_u64 v[36:37], v[128:129], 1, v[34:35]
	v_mov_b64_e32 v[34:35], v[128:129]
	s_or_b64 exec, exec, s[16:17]
	s_ashr_i32 s15, s14, 31
	s_lshl_b64 s[14:15], s[14:15], 11
	s_add_u32 s14, s12, s14
	s_addc_u32 s15, s13, s15
	v_lshl_add_u64 v[40:41], s[14:15], 0, v[138:139]
	v_lshl_add_u64 v[44:45], s[14:15], 0, v[140:141]
	global_load_dwordx4 v[36:39], v[36:37], off
	s_nop 0
	global_load_dwordx4 v[40:43], v[40:41], off offset:128
	s_nop 0
	global_load_dwordx4 v[44:47], v[44:45], off offset:128
	s_add_i32 s14, s19, 0x10040
	s_waitcnt vmcnt(0)
	ds_write_b128 v170, v[26:29]
	s_waitcnt vmcnt(3)
	ds_write_b128 v171, v[30:33]
	v_add_u32_e32 v26, s14, v152
	v_ashrrev_i32_e32 v27, 31, v26
	s_waitcnt vmcnt(2)
	ds_write_b128 v172, v[36:39]
	s_waitcnt vmcnt(1)
	ds_write_b128 v173, v[40:43] offset:13312
	s_waitcnt vmcnt(0)
	ds_write_b128 v173, v[44:47] offset:13504
	s_waitcnt lgkmcnt(0)
	s_barrier
	s_and_saveexec_b64 s[16:17], s[40:41]
	s_xor_b64 s[16:17], exec, s[16:17]
	s_movk_i32 s10, 0xff80
	v_mad_i64_i32 v[26:27], s[46:47], v26, s35, v[116:117]
	s_mov_b32 s11, -1
	v_lshl_add_u64 v[28:29], v[26:27], 0, s[10:11]
	s_or_saveexec_b64 s[16:17], s[16:17]
	v_lshl_add_u64 v[142:143], v[118:119], 1, s[12:13]
	s_xor_b64 exec, exec, s[16:17]
	v_lshlrev_b64 v[26:27], 11, v[26:27]
	v_lshl_add_u64 v[28:29], v[142:143], 0, v[26:27]
	s_or_b64 exec, exec, s[16:17]
	global_load_dwordx4 v[50:53], v[28:29], off
	v_add_u32_e32 v28, s14, v153
	v_ashrrev_i32_e32 v29, 31, v28
	s_and_saveexec_b64 s[16:17], s[42:43]
	s_xor_b64 s[16:17], exec, s[16:17]
	s_movk_i32 s10, 0xff80
	v_mad_i64_i32 v[26:27], s[46:47], v28, s35, v[120:121]
	s_mov_b32 s11, -1
	v_lshl_add_u64 v[26:27], v[26:27], 0, s[10:11]
	s_or_saveexec_b64 s[16:17], s[16:17]
	v_lshl_add_u64 v[144:145], v[122:123], 1, s[12:13]
	s_xor_b64 exec, exec, s[16:17]
	v_lshlrev_b64 v[26:27], 11, v[28:29]
	v_lshl_add_u64 v[26:27], v[144:145], 0, v[26:27]
	s_or_b64 exec, exec, s[16:17]
	global_load_dwordx4 v[54:57], v[26:27], off
	v_add_u32_e32 v28, s14, v154
	v_ashrrev_i32_e32 v29, 31, v28
	s_and_saveexec_b64 s[16:17], s[44:45]
	s_xor_b64 s[16:17], exec, s[16:17]
	s_movk_i32 s10, 0xff80
	v_mad_i64_i32 v[26:27], s[46:47], v28, s35, v[126:127]
	s_mov_b32 s11, -1
	v_lshl_add_u64 v[26:27], v[26:27], 0, s[10:11]
	s_or_saveexec_b64 s[16:17], s[16:17]
	v_lshl_add_u64 v[146:147], v[34:35], 1, s[12:13]
	s_xor_b64 exec, exec, s[16:17]
	v_lshlrev_b64 v[26:27], 11, v[28:29]
	v_lshl_add_u64 v[26:27], v[146:147], 0, v[26:27]
	s_or_b64 exec, exec, s[16:17]
	s_ashr_i32 s15, s14, 31
	s_lshl_b64 s[14:15], s[14:15], 11
	s_add_u32 s14, s12, s14
	s_addc_u32 s15, s13, s15
	global_load_dwordx4 v[58:61], v[26:27], off
	v_lshl_add_u64 v[26:27], s[14:15], 0, v[138:139]
	v_lshl_add_u64 v[28:29], s[14:15], 0, v[140:141]
	global_load_dwordx4 v[62:65], v[26:27], off offset:128
	global_load_dwordx4 v[90:93], v[28:29], off offset:128
	v_lshrrev_b32_e32 v113, 16, v5
	v_lshrrev_b32_e32 v175, 16, v4
	v_lshrrev_b32_e32 v176, 16, v3
	v_lshrrev_b32_e32 v177, 16, v2
	v_lshrrev_b32_e32 v178, 16, v9
	v_lshrrev_b32_e32 v179, 16, v8
	v_lshrrev_b32_e32 v180, 16, v7
	v_lshrrev_b32_e32 v181, 16, v6
	v_lshrrev_b32_e32 v182, 16, v13
	v_lshrrev_b32_e32 v183, 16, v12
	v_lshrrev_b32_e32 v184, 16, v11
	v_lshrrev_b32_e32 v185, 16, v10
	v_lshrrev_b32_e32 v77, 16, v17
	v_lshrrev_b32_e32 v76, 16, v16
	v_lshrrev_b32_e32 v75, 16, v15
	v_lshrrev_b32_e32 v74, 16, v14
	v_lshrrev_b32_e32 v73, 16, v21
	v_lshrrev_b32_e32 v72, 16, v20
	v_lshrrev_b32_e32 v71, 16, v19
	v_lshrrev_b32_e32 v70, 16, v18
	v_lshrrev_b32_e32 v26, 16, v25
	v_lshrrev_b32_e32 v27, 16, v24
	v_lshrrev_b32_e32 v28, 16, v23
	v_lshrrev_b32_e32 v29, 16, v22
	s_mov_b32 s10, 0x5040100
	v_perm_b32 v66, v29, v22, s10
	v_perm_b32 v67, v28, v23, s10
	v_perm_b32 v68, v27, v24, s10
	v_perm_b32 v69, v26, v25, s10
	ds_read_b128 v[22:25], v174
	ds_read_b128 v[42:45], v174 offset:32
	ds_read_b128 v[38:41], v174 offset:6656
	ds_read_b128 v[46:49], v174 offset:6688
	ds_read_b128 v[78:81], v174 offset:64
	ds_read_b128 v[94:97], v174 offset:6720
	ds_read_b128 v[82:85], v174 offset:96
	ds_read_b128 v[98:101], v174 offset:6752
	ds_read_b128 v[86:89], v174 offset:128
	ds_read_b128 v[102:105], v174 offset:6784
	ds_read_b128 v[106:109], v174 offset:160
	ds_read_b128 v[148:151], v174 offset:6816
	s_waitcnt lgkmcnt(11)
; DI f32x16 mfma32(bf16x8 a, bf16x8 b, f32x16 c) { return __builtin_amdgcn_mfma_f32_32x32x16_bf16(a, b, c, 0, 0, 0); }
; template <int DQK, int DV, int KW0, int MODE> ...
;     ...
;     {
;       bf16x8 kfa[DQK / 16], kfb[DQK / 16], qv[DQK / 16];
; #pragma unroll
;       for (int kk = 0; kk < DQK / 16; ++kk) {
;         kfa[kk] = *(const bf16x8*)(cur + r * (KS * 2) + kk * 32 + h * 16);
;         kfb[kk] = *(const bf16x8*)(cur + (32 + r) * (KS * 2) + kk * 32 + h * 16);
;         qv[kk] = QLDS ? *(const bf16x8*)(qbase + kk * 1024) : qf[kk];
;       }
; #pragma unroll
;       for (int kk = 0; kk < DQK / 16; ++kk) {
;         S0 = mfma32(kfa[kk], qv[kk], S0);
;         S1 = mfma32(kfb[kk], qv[kk], S1);
;       }
;       __builtin_amdgcn_sched_group_barrier(0x100, (QLDS ? 3 : 2) * (DQK / 16), 0);
;       __builtin_amdgcn_sched_group_barrier(0x008, 2 * (DQK / 16), 0);
;     }
;     if (MODE == 2) {
;       if (it >= 4) {
;         const int w = wlo + it - 4;
;         if (w < 2 || w > 3) {
;           const int kpos0 = (qn - 1) * 128 + 64 * w, qpos = qn * 128 + wid * 32 + r;
; #pragma unroll
;           for (int e = 0; e < 16; ++e) {
;             const int d0 = qpos - (kpos0 + crow(e, h)), d1 = d0 - 32;
;             if (d0 > 128 || d0 < -128) S0[e] = -1e30f;
;             if (d1 > 128 || d1 < -128) S1[e] = -1e30f;
;           }
;         }
;       }
;     }
;     float mx = S0[0];
; #pragma unroll
;     for (int e = 1; e < 16; ++e) mx = fmaxf(mx, S0[e]);
; #pragma unroll
;     for (int e = 0; e < 16; ++e) mx = fmaxf(mx, S1[e]);
;     mx = fmaxf(mx, __shfl_xor(mx, 32));
;     const float mn = fmaxf(m, mx);
;     const bool grow = __builtin_amdgcn_ballot_w64(mx > m) != 0ull;
;     const float alpha = __builtin_amdgcn_exp2f((m - mn) * c);
;     m = mn;
;     const float mc = mn * c;
;     float ps = 0.f;
; #pragma unroll
;     for (int e = 0; e < 16; ++e) { S0[e] = __builtin_amdgcn_exp2f(S0[e] * c - mc); ps += S0[e]; }
; #pragma unroll
;     for (int e = 0; e < 16; ++e) { S1[e] = __builtin_amdgcn_exp2f(S1[e] * c - mc); ps += S1[e]; }
;     if (grow) {
;       l *= alpha;
; #pragma unroll
;       for (int t = 0; t < DV / 32; ++t)
; #pragma unroll
;         for (int e = 0; e < 16; ++e) O[t][e] *= alpha;
;     }
;     l += ps;
;     bf16x8 pf[2][2];
; #pragma unroll
;     for (int s = 0; s < 2; ++s) {
;       u32x4 w0, w1;
	v_mfma_f32_32x32x16_bf16 v[22:37], v[22:25], v[66:69], 0
	v_perm_b32 v70, v70, v18, s10
	v_perm_b32 v71, v71, v19, s10
	v_perm_b32 v72, v72, v20, s10
	v_perm_b32 v73, v73, v21, s10
	v_perm_b32 v74, v74, v14, s10
	v_perm_b32 v75, v75, v15, s10
	v_perm_b32 v76, v76, v16, s10
	s_waitcnt lgkmcnt(10)
	v_mfma_f32_32x32x16_bf16 v[22:37], v[42:45], v[70:73], v[22:37]
	v_perm_b32 v77, v77, v17, s10
	s_waitcnt lgkmcnt(7)
	s_nop 0
	v_mfma_f32_32x32x16_bf16 v[22:37], v[78:81], v[74:77], v[22:37]
	v_perm_b32 v78, v185, v10, s10
	v_perm_b32 v79, v184, v11, s10
	v_perm_b32 v80, v183, v12, s10
	v_perm_b32 v81, v182, v13, s10
	s_waitcnt lgkmcnt(5)
	s_nop 0
	v_mfma_f32_32x32x16_bf16 v[22:37], v[82:85], v[78:81], v[22:37]
	v_perm_b32 v82, v181, v6, s10
	v_perm_b32 v83, v180, v7, s10
	v_perm_b32 v84, v179, v8, s10
	v_perm_b32 v85, v178, v9, s10
	v_mfma_f32_32x32x16_bf16 v[6:21], v[38:41], v[66:69], 0
	v_mfma_f32_32x32x16_bf16 v[6:21], v[46:49], v[70:73], v[6:21]
	v_mfma_f32_32x32x16_bf16 v[6:21], v[94:97], v[74:77], v[6:21]
	s_waitcnt lgkmcnt(3)
	v_mfma_f32_32x32x16_bf16 v[22:37], v[86:89], v[82:85], v[22:37]
	v_perm_b32 v86, v177, v2, s10
	v_perm_b32 v87, v176, v3, s10
	v_perm_b32 v88, v175, v4, s10
	v_perm_b32 v89, v113, v5, s10
	s_mov_b32 s10, 0xf149f2ca
	v_mfma_f32_32x32x16_bf16 v[6:21], v[98:101], v[78:81], v[6:21]
	s_waitcnt lgkmcnt(1)
	v_mfma_f32_32x32x16_bf16 v[22:37], v[106:109], v[86:89], v[22:37]
	v_mfma_f32_32x32x16_bf16 v[6:21], v[102:105], v[82:85], v[6:21]
	s_nop 10
	v_max_f32_e32 v2, v23, v23
	v_max_f32_e32 v3, v22, v22
	v_max_f32_e32 v2, v3, v2
	v_max3_f32 v2, v2, v24, v25
	v_max3_f32 v2, v2, v26, v27
	v_max3_f32 v2, v2, v28, v29
	v_max3_f32 v2, v2, v30, v31
	s_waitcnt lgkmcnt(0)
	v_mfma_f32_32x32x16_bf16 v[6:21], v[148:151], v[86:89], v[6:21]
	v_max3_f32 v2, v2, v32, v33
	v_max3_f32 v2, v2, v34, v35
	v_max3_f32 v2, v2, v36, v37
	s_nop 8
	v_max3_f32 v2, v2, v6, v7
	v_max3_f32 v2, v2, v8, v9
	v_max3_f32 v2, v2, v10, v11
	v_max3_f32 v2, v2, v12, v13
	v_max3_f32 v2, v2, v14, v15
	v_max3_f32 v2, v2, v16, v17
	v_max3_f32 v2, v2, v18, v19
	v_max3_f32 v2, v2, v20, v21
	v_mov_b32_e32 v3, v2
	s_nop 1
	v_permlane32_swap_b32_e32 v3, v2
	v_mov_b32_e32 v148, v21
	s_waitcnt lgkmcnt(0)
	v_max_f32_e32 v2, v2, v3
	v_max_f32_e32 v149, 0xf149f2ca, v2
	v_pk_mul_f32 v[196:197], v[148:149], s[30:31] op_sel_hi:[1,0]
	v_cmp_lt_f32_e32 vcc, s10, v2
	v_fma_f32 v2, v22, s30, -v197
	v_exp_f32_e32 v98, v2
	v_fma_f32 v2, v23, s30, -v197
	v_exp_f32_e32 v99, v2
	v_fma_f32 v2, v24, s30, -v197
	v_exp_f32_e32 v100, v2
	v_fma_f32 v2, v25, s30, -v197
	v_exp_f32_e32 v101, v2
	v_fma_f32 v2, v26, s30, -v197
	v_exp_f32_e32 v102, v2
	v_fma_f32 v2, v27, s30, -v197
	v_exp_f32_e32 v103, v2
	v_fma_f32 v2, v28, s30, -v197
	v_exp_f32_e32 v104, v2
	v_fma_f32 v2, v29, s30, -v197
	v_exp_f32_e32 v105, v2
	v_fma_f32 v2, v30, s30, -v197
	v_exp_f32_e32 v106, v2
	v_fma_f32 v2, v31, s30, -v197
	v_exp_f32_e32 v107, v2
	v_fma_f32 v2, v32, s30, -v197
	v_exp_f32_e32 v108, v2
	v_fma_f32 v2, v33, s30, -v197
	v_exp_f32_e32 v109, v2
	v_fma_f32 v2, v34, s30, -v197
	v_exp_f32_e32 v113, v2
	v_fma_f32 v2, v35, s30, -v197
	v_exp_f32_e32 v148, v2
	v_fma_f32 v2, v36, s30, -v197
	v_exp_f32_e32 v150, v2
	v_fma_f32 v2, v37, s30, -v197
	v_exp_f32_e32 v151, v2
	v_fma_f32 v2, v6, s30, -v197
	v_exp_f32_e32 v175, v2
	v_fma_f32 v2, v7, s30, -v197
	v_exp_f32_e32 v176, v2
	v_fma_f32 v2, v8, s30, -v197
	v_exp_f32_e32 v177, v2
	v_fma_f32 v2, v9, s30, -v197
	v_exp_f32_e32 v178, v2
	v_fma_f32 v2, v10, s30, -v197
	v_exp_f32_e32 v179, v2
	v_fma_f32 v2, v11, s30, -v197
	v_exp_f32_e32 v180, v2
	v_fma_f32 v2, v12, s30, -v197
	v_exp_f32_e32 v181, v2
	v_fma_f32 v2, v13, s30, -v197
	v_exp_f32_e32 v182, v2
	v_fma_f32 v2, v14, s30, -v197
	v_exp_f32_e32 v183, v2
	v_fma_f32 v2, v15, s30, -v197
	v_exp_f32_e32 v184, v2
	v_sub_f32_e32 v2, 0xf149f2ca, v149
	v_mul_f32_e32 v2, 0x3e16c740, v2
	v_exp_f32_e32 v2, v2
	s_cmp_eq_u64 vcc, 0
	s_cselect_b64 s[14:15], -1, 0
	v_fma_f32 v3, v16, s30, -v197
	v_mul_f32_e32 v2, 0, v2
	v_cndmask_b32_e64 v34, v2, 0, s[14:15]
	v_cvt_pk_bf16_f32 v94, v98, v99
	v_cvt_pk_bf16_f32 v95, v100, v101
	v_cvt_pk_bf16_f32 v96, v102, v103
	v_cvt_pk_bf16_f32 v97, v104, v105
	v_mov_b32_e32 v35, v34
	v_mov_b32_e32 v36, v34
	v_mov_b32_e32 v37, v34
	v_mov_b32_e32 v38, v34
	v_mov_b32_e32 v39, v34
	v_mov_b32_e32 v40, v34
	v_mov_b32_e32 v41, v34
	v_mov_b32_e32 v42, v34
	v_mov_b32_e32 v43, v34
	v_mov_b32_e32 v44, v34
	v_mov_b32_e32 v45, v34
	v_mov_b32_e32 v46, v34
	v_mov_b32_e32 v47, v34
	v_mov_b32_e32 v48, v34
	v_mov_b32_e32 v49, v34
	v_exp_f32_e32 v185, v3
	v_fma_f32 v21, v17, s30, -v197
	ds_read_b64_tr_b16 v[192:193], v168 offset:0
	ds_read_b64_tr_b16 v[194:195], v168 offset:1536
	ds_read_b64_tr_b16 v[30:31], v168 offset:3072
	ds_read_b64_tr_b16 v[32:33], v168 offset:4608
	ds_read_b64_tr_b16 v[26:27], v168 offset:6144
	ds_read_b64_tr_b16 v[28:29], v168 offset:7680
	ds_read_b64_tr_b16 v[22:23], v168 offset:9216
	ds_read_b64_tr_b16 v[24:25], v168 offset:10752
	s_waitcnt lgkmcnt(0)
	v_cvt_pk_bf16_f32 v218, v106, v107
	v_mfma_f32_32x32x16_bf16 v[2:17], v[192:195], v[94:97], v[34:49]
	v_cvt_pk_bf16_f32 v219, v108, v109
	v_cvt_pk_bf16_f32 v220, v113, v148
	v_cvt_pk_bf16_f32 v221, v150, v151
	v_fma_f32 v18, v18, s30, -v197
	v_cvt_pk_bf16_f32 v222, v175, v176
	v_cvt_pk_bf16_f32 v223, v177, v178
	v_cvt_pk_bf16_f32 v224, v179, v180
	v_mfma_f32_32x32x16_bf16 v[2:17], v[30:33], v[218:221], v[2:17]
	v_cvt_pk_bf16_f32 v225, v181, v182
	v_exp_f32_e32 v192, v18
	v_fma_f32 v18, v19, s30, -v197
	v_exp_f32_e32 v193, v18
	v_fma_f32 v18, v20, s30, -v197
	v_exp_f32_e32 v194, v18
	v_sub_f32_e32 v18, v196, v197
	v_mfma_f32_32x32x16_bf16 v[2:17], v[26:29], v[222:225], v[2:17]
	v_exp_f32_e32 v189, v21
	v_exp_f32_e32 v195, v18
	v_cvt_pk_bf16_f32 v226, v183, v184
	v_cvt_pk_bf16_f32 v228, v192, v193
	v_cvt_pk_bf16_f32 v227, v185, v189
	v_cvt_pk_bf16_f32 v229, v194, v195
	ds_read_b64_tr_b16 v[242:243], v168 offset:64
	ds_read_b64_tr_b16 v[244:245], v168 offset:1600
	ds_read_b64_tr_b16 v[238:239], v168 offset:3136
	ds_read_b64_tr_b16 v[240:241], v168 offset:4672
	ds_read_b64_tr_b16 v[234:235], v168 offset:6208
	ds_read_b64_tr_b16 v[236:237], v168 offset:7744
	ds_read_b64_tr_b16 v[230:231], v168 offset:9280
	ds_read_b64_tr_b16 v[232:233], v168 offset:10816
	s_waitcnt lgkmcnt(0)
; DI unsigned pk2(float a, float b) { f32x2 v = {a, b}; bf2_t r = __builtin_convertvector(v, bf2_t); return __builtin_bit_cast(unsigned, r); }
; template <int DQK, int DV, int KW0, int MODE> ...
;     ...
;     float mx = S0[0];
; #pragma unroll
;     for (int e = 1; e < 16; ++e) mx = fmaxf(mx, S0[e]);
; #pragma unroll
;     for (int e = 0; e < 16; ++e) mx = fmaxf(mx, S1[e]);
;     mx = fmaxf(mx, __shfl_xor(mx, 32));
;     const float mn = fmaxf(m, mx);
;     const bool grow = __builtin_amdgcn_ballot_w64(mx > m) != 0ull;
;     const float alpha = __builtin_amdgcn_exp2f((m - mn) * c);
;     m = mn;
;     const float mc = mn * c;
;     float ps = 0.f;
; #pragma unroll
;     for (int e = 0; e < 16; ++e) { S0[e] = __builtin_amdgcn_exp2f(S0[e] * c - mc); ps += S0[e]; }
; #pragma unroll
;     for (int e = 0; e < 16; ++e) { S1[e] = __builtin_amdgcn_exp2f(S1[e] * c - mc); ps += S1[e]; }
;     if (grow) {
;       l *= alpha;
; #pragma unroll
;       for (int t = 0; t < DV / 32; ++t)
; #pragma unroll
;         for (int e = 0; e < 16; ++e) O[t][e] *= alpha;
;     }
;     l += ps;
;     bf16x8 pf[2][2];
; #pragma unroll
;     for (int s = 0; s < 2; ++s) {
;       u32x4 w0, w1;
;       w0.x = pk2(S0[8 * s + 0], S0[8 * s + 1]); w0.y = pk2(S0[8 * s + 2], S0[8 * s + 3]); w0.z = pk2(S0[8 * s + 4], S0[8 * s + 5]); w0.w = pk2(S0[8 * s + 6], S0[8 * s + 7]);
;       w1.x = pk2(S1[8 * s + 0], S1[8 * s + 1]); w1.y = pk2(S1[8 * s + 2], S1[8 * s + 3]); w1.z = pk2(S1[8 * s + 4], S1[8 * s + 5]); w1.w = pk2(S1[8 * s + 6], S1[8 * s + 7]);
;       pf[0][s] = __builtin_bit_cast(bf16x8, w0); pf[1][s] = __builtin_bit_cast(bf16x8, w1);
;     }
;     {
;       const unsigned vaddr = (unsigned)(size_t)(cur + KB) + (unsigned)((4 * h + ((lane & 15) >> 2)) * VSB + ((lane >> 4) & 1) * 32 + (lane & 3) * 8);
;       if (DV == 64) {
;         s16x4 R[8];
;     ...
;         PV_TILE64_(0); PV_TILE64_(1);
;     ...
;       } else {
;         s16x4 R[8];
;     ...
;         PV_TILE_(0); PV_TILE_(1); PV_TILE_(2); PV_TILE_(3);
;     ...
;       }
;     }
;     if (DV > 64) { __builtin_amdgcn_sched_barrier(0); if (more) attn_gload<DQK, DV, KW0, 3>(kreg, vreg, k0p, ldk0, k1p, ldk1, vp, ldv, key_tile_row<MODE>(it + 1, b, qn, wlo), tid); }
;     if (more) attn_sstore<DQK, DV>(kreg, vreg, smem + ((it + 1) & 1) * STG, tid);
	s_add_i32 s14, s19, 0x10080
	s_waitcnt vmcnt(4)
	ds_write_b128 v170, v[50:53] offset:25600
	v_mfma_f32_32x32x16_bf16 v[2:17], v[22:25], v[226:229], v[2:17]
	v_mov_b64_e32 v[18:19], v[34:35]
	v_mov_b64_e32 v[20:21], v[36:37]
	v_mov_b64_e32 v[22:23], v[38:39]
	v_mov_b64_e32 v[24:25], v[40:41]
	v_mov_b64_e32 v[26:27], v[42:43]
	v_mov_b64_e32 v[28:29], v[44:45]
	v_mov_b64_e32 v[30:31], v[46:47]
	v_mov_b64_e32 v[32:33], v[48:49]
	v_add_u32_e32 v38, s14, v152
	v_ashrrev_i32_e32 v39, 31, v38
	v_mfma_f32_32x32x16_bf16 v[18:33], v[242:245], v[94:97], v[18:33]
	s_waitcnt vmcnt(3)
	ds_write_b128 v171, v[54:57] offset:25600
	s_waitcnt vmcnt(2)
	ds_write_b128 v172, v[58:61] offset:25600
	s_waitcnt vmcnt(1)
	ds_write_b128 v173, v[62:65] offset:38912
	s_waitcnt vmcnt(0)
	ds_write_b128 v173, v[90:93] offset:39104
	s_waitcnt lgkmcnt(0)
	s_barrier
	v_mfma_f32_32x32x16_bf16 v[18:33], v[238:241], v[218:221], v[18:33]
	v_mfma_f32_32x32x16_bf16 v[18:33], v[234:237], v[222:225], v[18:33]
	v_mfma_f32_32x32x16_bf16 v[18:33], v[230:233], v[226:229], v[18:33]
	s_and_saveexec_b64 s[16:17], s[40:41]
	s_xor_b64 s[16:17], exec, s[16:17]
	s_movk_i32 s10, 0xff80
	v_mad_i64_i32 v[36:37], s[46:47], v38, s35, v[116:117]
	s_mov_b32 s11, -1
	v_lshl_add_u64 v[36:37], v[36:37], 0, s[10:11]
	s_andn2_saveexec_b64 s[16:17], s[16:17]
	v_lshlrev_b64 v[36:37], 11, v[38:39]
	v_lshl_add_u64 v[36:37], v[142:143], 0, v[36:37]
	s_or_b64 exec, exec, s[16:17]
	global_load_dwordx4 v[90:93], v[36:37], off
	v_add_u32_e32 v38, s14, v153
	v_ashrrev_i32_e32 v39, 31, v38
	s_and_saveexec_b64 s[16:17], s[42:43]
	s_xor_b64 s[16:17], exec, s[16:17]
	s_movk_i32 s10, 0xff80
	v_mad_i64_i32 v[36:37], s[46:47], v38, s35, v[120:121]
	s_mov_b32 s11, -1
	v_lshl_add_u64 v[36:37], v[36:37], 0, s[10:11]
	s_andn2_saveexec_b64 s[16:17], s[16:17]
	v_lshlrev_b64 v[36:37], 11, v[38:39]
	v_lshl_add_u64 v[36:37], v[144:145], 0, v[36:37]
	s_or_b64 exec, exec, s[16:17]
	global_load_dwordx4 v[94:97], v[36:37], off
	v_add_u32_e32 v38, s14, v154
	v_ashrrev_i32_e32 v39, 31, v38
	s_and_saveexec_b64 s[16:17], s[44:45]
	s_xor_b64 s[16:17], exec, s[16:17]
	s_movk_i32 s10, 0xff80
	v_mad_i64_i32 v[36:37], s[46:47], v38, s35, v[126:127]
	s_mov_b32 s11, -1
	v_lshl_add_u64 v[36:37], v[36:37], 0, s[10:11]
	s_andn2_saveexec_b64 s[16:17], s[16:17]
	v_lshlrev_b64 v[36:37], 11, v[38:39]
	v_lshl_add_u64 v[36:37], v[146:147], 0, v[36:37]
	s_or_b64 exec, exec, s[16:17]
	v_add_f32_e32 v35, 0, v98
	v_add_f32_e32 v35, v99, v35
	v_add_f32_e32 v35, v100, v35
	v_add_f32_e32 v35, v101, v35
	v_add_f32_e32 v35, v102, v35
	v_add_f32_e32 v35, v103, v35
	v_add_f32_e32 v35, v104, v35
	v_add_f32_e32 v35, v105, v35
	v_add_f32_e32 v35, v106, v35
	v_add_f32_e32 v35, v107, v35
	v_add_f32_e32 v35, v108, v35
	v_add_f32_e32 v35, v109, v35
	v_add_f32_e32 v35, v113, v35
	v_add_f32_e32 v35, v148, v35
	v_add_f32_e32 v35, v150, v35
	v_add_f32_e32 v35, v151, v35
	v_add_f32_e32 v35, v175, v35
	v_add_f32_e32 v35, v176, v35
	v_add_f32_e32 v35, v177, v35
	v_add_f32_e32 v35, v178, v35
	v_add_f32_e32 v35, v179, v35
	v_add_f32_e32 v35, v180, v35
	v_add_f32_e32 v35, v181, v35
	v_add_f32_e32 v35, v182, v35
	v_add_f32_e32 v35, v183, v35
	v_add_f32_e32 v35, v184, v35
	v_add_f32_e32 v35, v185, v35
	v_add_f32_e32 v35, v189, v35
	v_add_f32_e32 v35, v192, v35
	s_ashr_i32 s15, s14, 31
	v_add_f32_e32 v35, v193, v35
	s_lshl_b64 s[14:15], s[14:15], 11
	v_add_f32_e32 v35, v194, v35
	s_add_u32 s14, s12, s14
	v_add_f32_e32 v35, v195, v35
	s_addc_u32 s15, s13, s15
	v_add_f32_e32 v113, v35, v34
	v_lshl_add_u64 v[34:35], s[14:15], 0, v[138:139]
	global_load_dwordx4 v[102:105], v[34:35], off offset:128
	v_lshl_add_u64 v[34:35], s[14:15], 0, v[140:141]
	global_load_dwordx4 v[98:101], v[36:37], off
	global_load_dwordx4 v[106:109], v[34:35], off offset:128
	ds_read_b128 v[38:41], v174 offset:25600
	ds_read_b128 v[42:45], v174 offset:25632
	ds_read_b128 v[34:37], v174 offset:32256
	ds_read_b128 v[176:179], v174 offset:32288
	ds_read_b128 v[46:49], v174 offset:25664
	ds_read_b128 v[180:183], v174 offset:32320
	ds_read_b128 v[192:195], v174 offset:25696
	ds_read_b128 v[218:221], v174 offset:32352
	ds_read_b128 v[222:225], v174 offset:25728
	ds_read_b128 v[226:229], v174 offset:32384
	ds_read_b128 v[230:233], v174 offset:25760
	ds_read_b128 v[234:237], v174 offset:32416
	s_waitcnt lgkmcnt(11)
	v_mfma_f32_32x32x16_bf16 v[50:65], v[38:41], v[66:69], 0
	s_waitcnt lgkmcnt(10)
	v_mfma_f32_32x32x16_bf16 v[50:65], v[42:45], v[70:73], v[50:65]
	s_waitcnt lgkmcnt(7)
	v_mfma_f32_32x32x16_bf16 v[50:65], v[46:49], v[74:77], v[50:65]
	v_mfma_f32_32x32x16_bf16 v[34:49], v[34:37], v[66:69], 0
	v_mfma_f32_32x32x16_bf16 v[34:49], v[176:179], v[70:73], v[34:49]
	s_waitcnt lgkmcnt(5)
	v_mfma_f32_32x32x16_bf16 v[50:65], v[192:195], v[78:81], v[50:65]
	v_mfma_f32_32x32x16_bf16 v[34:49], v[180:183], v[74:77], v[34:49]
	s_waitcnt lgkmcnt(3)
	v_mfma_f32_32x32x16_bf16 v[50:65], v[222:225], v[82:85], v[50:65]
	v_mfma_f32_32x32x16_bf16 v[34:49], v[218:221], v[78:81], v[34:49]
	s_waitcnt lgkmcnt(1)
	v_mfma_f32_32x32x16_bf16 v[50:65], v[230:233], v[86:89], v[50:65]
	v_mfma_f32_32x32x16_bf16 v[34:49], v[226:229], v[82:85], v[34:49]
	s_nop 10
	v_max_f32_e32 v148, v51, v51
	v_max_f32_e32 v150, v50, v50
	v_max_f32_e32 v148, v150, v148
	v_max3_f32 v148, v148, v52, v53
	v_max3_f32 v148, v148, v54, v55
	v_max3_f32 v148, v148, v56, v57
	v_max3_f32 v148, v148, v58, v59
	s_waitcnt lgkmcnt(0)
	v_mfma_f32_32x32x16_bf16 v[34:49], v[234:237], v[86:89], v[34:49]
	v_max3_f32 v148, v148, v60, v61
	v_max3_f32 v148, v148, v62, v63
	v_max3_f32 v148, v148, v64, v65
	s_nop 8
	v_max3_f32 v148, v148, v34, v35
	v_max3_f32 v148, v148, v36, v37
	v_max3_f32 v148, v148, v38, v39
	v_max3_f32 v148, v148, v40, v41
	v_max3_f32 v148, v148, v42, v43
	v_max3_f32 v148, v148, v44, v45
	v_max3_f32 v148, v148, v46, v47
	v_max3_f32 v148, v148, v48, v49
	v_mov_b32_e32 v150, v148
	s_nop 1
	v_permlane32_swap_b32_e32 v150, v148
	s_waitcnt lgkmcnt(0)
	v_max_f32_e32 v150, v148, v150
	v_max_f32_e32 v148, v149, v149
	v_max_f32_e32 v148, v148, v150
	v_cmp_gt_f32_e32 vcc, v150, v149
	s_cbranch_vccz .LBB0_105
; DI unsigned pk2(float a, float b) { f32x2 v = {a, b}; bf2_t r = __builtin_convertvector(v, bf2_t); return __builtin_bit_cast(unsigned, r); }
; #define PV_TILE64_(T) do { TRV8_192_T##T(R, vaddr); \
;           _Pragma("unroll") for (int st = 0; st < 2; ++st) _Pragma("unroll") for (int s = 0; s < 2; ++s) { const int ix = (st * 2 + s) * 2; \
;             const bf16x8 va = __builtin_shufflevector(R[ix], R[ix + 1], 0, 1, 2, 3, 4, 5, 6, 7); O[T] = mfma32(va, pf[st][s], O[T]); } } while (0)
; #define PV_TILE_(T) do { TRV8_320_T##T(R, vaddr); \
;           _Pragma("unroll") for (int st = 0; st < 2; ++st) _Pragma("unroll") for (int s = 0; s < 2; ++s) { const int ix = (st * 2 + s) * 2; \
;             const bf16x8 va = __builtin_shufflevector(R[ix], R[ix + 1], 0, 1, 2, 3, 4, 5, 6, 7); O[(DV > 64) ? T : 0] = mfma32(va, pf[st][s], O[(DV > 64) ? T : 0]); } } while (0)
; template <int DQK, int DV, int KW0, int MODE> ...
;     ...
;     if (grow) {
;       l *= alpha;
; #pragma unroll
;       for (int t = 0; t < DV / 32; ++t)
; #pragma unroll
;         for (int e = 0; e < 16; ++e) O[t][e] *= alpha;
;     }
;     l += ps;
;     bf16x8 pf[2][2];
; #pragma unroll
;     for (int s = 0; s < 2; ++s) {
;       u32x4 w0, w1;
;       w0.x = pk2(S0[8 * s + 0], S0[8 * s + 1]); w0.y = pk2(S0[8 * s + 2], S0[8 * s + 3]); w0.z = pk2(S0[8 * s + 4], S0[8 * s + 5]); w0.w = pk2(S0[8 * s + 6], S0[8 * s + 7]);
;       w1.x = pk2(S1[8 * s + 0], S1[8 * s + 1]); w1.y = pk2(S1[8 * s + 2], S1[8 * s + 3]); w1.z = pk2(S1[8 * s + 4], S1[8 * s + 5]); w1.w = pk2(S1[8 * s + 6], S1[8 * s + 7]);
;       pf[0][s] = __builtin_bit_cast(bf16x8, w0); pf[1][s] = __builtin_bit_cast(bf16x8, w1);
;     }
;     {
;       const unsigned vaddr = (unsigned)(size_t)(cur + KB) + (unsigned)((4 * h + ((lane & 15) >> 2)) * VSB + ((lane >> 4) & 1) * 32 + (lane & 3) * 8);
;       if (DV == 64) {
;         s16x4 R[8];
;     ...
;         PV_TILE64_(0); PV_TILE64_(1);
;     ...
;       } else {
;         s16x4 R[8];
;     ...
;         PV_TILE_(0); PV_TILE_(1); PV_TILE_(2); PV_TILE_(3);
;     ...
;       }
;     }
;     if (DV > 64) { __builtin_amdgcn_sched_barrier(0); if (more) attn_gload<DQK, DV, KW0, 3>(kreg, vreg, k0p, ldk0, k1p, ldk1, vp, ldv, key_tile_row<MODE>(it + 1, b, qn, wlo), tid); }
;     if (more) attn_sstore<DQK, DV>(kreg, vreg, smem + ((it + 1) & 1) * STG, tid);
	v_sub_f32_e32 v149, v149, v148
	v_mul_f32_e32 v149, 0x3e16c740, v149
	v_exp_f32_e32 v150, v149
	s_nop 0
	v_pk_mul_f32 v[32:33], v[32:33], v[150:151] op_sel_hi:[1,0]
	v_pk_mul_f32 v[30:31], v[30:31], v[150:151] op_sel_hi:[1,0]
	v_pk_mul_f32 v[28:29], v[28:29], v[150:151] op_sel_hi:[1,0]
	v_pk_mul_f32 v[26:27], v[26:27], v[150:151] op_sel_hi:[1,0]
	v_pk_mul_f32 v[24:25], v[24:25], v[150:151] op_sel_hi:[1,0]
	v_pk_mul_f32 v[22:23], v[22:23], v[150:151] op_sel_hi:[1,0]
	v_pk_mul_f32 v[20:21], v[20:21], v[150:151] op_sel_hi:[1,0]
	v_pk_mul_f32 v[18:19], v[18:19], v[150:151] op_sel_hi:[1,0]
	v_pk_mul_f32 v[16:17], v[16:17], v[150:151] op_sel_hi:[1,0]
	v_pk_mul_f32 v[14:15], v[14:15], v[150:151] op_sel_hi:[1,0]
	v_pk_mul_f32 v[12:13], v[12:13], v[150:151] op_sel_hi:[1,0]
	v_pk_mul_f32 v[10:11], v[10:11], v[150:151] op_sel_hi:[1,0]
	v_pk_mul_f32 v[8:9], v[8:9], v[150:151] op_sel_hi:[1,0]
	v_pk_mul_f32 v[6:7], v[6:7], v[150:151] op_sel_hi:[1,0]
	v_pk_mul_f32 v[4:5], v[4:5], v[150:151] op_sel_hi:[1,0]
	v_pk_mul_f32 v[2:3], v[2:3], v[150:151] op_sel_hi:[1,0]
	v_mul_f32_e32 v113, v113, v150
.LBB0_105:
	v_mul_f32_e32 v176, 0x3e16c740, v148
	v_fma_f32 v34, v34, s30, -v176
	v_exp_f32_e32 v149, v34
	v_fma_f32 v34, v35, s30, -v176
	v_exp_f32_e32 v150, v34
	v_fma_f32 v34, v36, s30, -v176
	v_exp_f32_e32 v151, v34
	v_fma_f32 v34, v37, s30, -v176
	v_exp_f32_e32 v175, v34
	v_fma_f32 v34, v38, s30, -v176
	v_exp_f32_e32 v38, v34
	v_fma_f32 v34, v39, s30, -v176
	v_exp_f32_e32 v39, v34
	v_fma_f32 v34, v40, s30, -v176
	v_exp_f32_e32 v40, v34
	v_fma_f32 v34, v41, s30, -v176
	v_exp_f32_e32 v41, v34
	v_fma_f32 v34, v42, s30, -v176
	v_exp_f32_e32 v42, v34
	v_fma_f32 v34, v43, s30, -v176
	v_exp_f32_e32 v43, v34
	v_fma_f32 v34, v44, s30, -v176
	v_fma_f32 v50, v50, s30, -v176
	v_fma_f32 v51, v51, s30, -v176
	v_fma_f32 v52, v52, s30, -v176
	v_fma_f32 v53, v53, s30, -v176
	v_fma_f32 v54, v54, s30, -v176
	v_fma_f32 v55, v55, s30, -v176
	v_fma_f32 v56, v56, s30, -v176
	v_fma_f32 v57, v57, s30, -v176
	v_exp_f32_e32 v44, v34
	v_fma_f32 v34, v45, s30, -v176
	v_exp_f32_e32 v50, v50
	v_exp_f32_e32 v51, v51
	v_exp_f32_e32 v52, v52
	v_exp_f32_e32 v53, v53
	v_exp_f32_e32 v54, v54
	v_exp_f32_e32 v55, v55
	v_exp_f32_e32 v56, v56
	v_exp_f32_e32 v57, v57
	v_exp_f32_e32 v45, v34
	v_fma_f32 v34, v46, s30, -v176
	v_exp_f32_e32 v46, v34
	v_fma_f32 v34, v47, s30, -v176
	v_exp_f32_e32 v47, v34
	v_fma_f32 v34, v48, s30, -v176
	v_exp_f32_e32 v48, v34
	v_fma_f32 v34, v49, s30, -v176
	v_exp_f32_e32 v49, v34
	v_cvt_pk_bf16_f32 v34, v50, v51
	v_cvt_pk_bf16_f32 v35, v52, v53
	v_cvt_pk_bf16_f32 v36, v54, v55
	v_cvt_pk_bf16_f32 v37, v56, v57
	ds_read_b64_tr_b16 v[230:231], v169 offset:0
	ds_read_b64_tr_b16 v[232:233], v169 offset:1536
	ds_read_b64_tr_b16 v[226:227], v169 offset:3072
	ds_read_b64_tr_b16 v[228:229], v169 offset:4608
	ds_read_b64_tr_b16 v[222:223], v169 offset:6144
	ds_read_b64_tr_b16 v[224:225], v169 offset:7680
	ds_read_b64_tr_b16 v[218:219], v169 offset:9216
	ds_read_b64_tr_b16 v[220:221], v169 offset:10752
	s_waitcnt lgkmcnt(0)
	v_fma_f32 v58, v58, s30, -v176
	v_fma_f32 v59, v59, s30, -v176
	v_mfma_f32_32x32x16_bf16 v[2:17], v[230:233], v[34:37], v[2:17]
	v_fma_f32 v60, v60, s30, -v176
	v_fma_f32 v61, v61, s30, -v176
	v_fma_f32 v62, v62, s30, -v176
	v_fma_f32 v63, v63, s30, -v176
	v_fma_f32 v64, v64, s30, -v176
	v_fma_f32 v65, v65, s30, -v176
	v_exp_f32_e32 v58, v58
	v_exp_f32_e32 v59, v59
	v_exp_f32_e32 v60, v60
	v_exp_f32_e32 v61, v61
	v_exp_f32_e32 v62, v62
	v_exp_f32_e32 v63, v63
	v_exp_f32_e32 v64, v64
	v_exp_f32_e32 v65, v65
	v_cvt_pk_bf16_f32 v180, v58, v59
	v_cvt_pk_bf16_f32 v181, v60, v61
	v_cvt_pk_bf16_f32 v182, v62, v63
	v_cvt_pk_bf16_f32 v183, v64, v65
	v_cvt_pk_bf16_f32 v176, v149, v150
	v_cvt_pk_bf16_f32 v177, v151, v175
	v_mfma_f32_32x32x16_bf16 v[2:17], v[226:229], v[180:183], v[2:17]
	v_cvt_pk_bf16_f32 v178, v38, v39
	v_cvt_pk_bf16_f32 v179, v40, v41
	v_cvt_pk_bf16_f32 v192, v42, v43
	v_cvt_pk_bf16_f32 v193, v44, v45
	v_cvt_pk_bf16_f32 v194, v46, v47
	v_cvt_pk_bf16_f32 v195, v48, v49
	s_add_i32 s14, s19, 0x100c0
	v_mfma_f32_32x32x16_bf16 v[2:17], v[222:225], v[176:179], v[2:17]
	v_mfma_f32_32x32x16_bf16 v[2:17], v[218:221], v[192:195], v[2:17]
	ds_read_b64_tr_b16 v[230:231], v169 offset:64
	ds_read_b64_tr_b16 v[232:233], v169 offset:1600
	ds_read_b64_tr_b16 v[226:227], v169 offset:3136
	ds_read_b64_tr_b16 v[228:229], v169 offset:4672
	ds_read_b64_tr_b16 v[222:223], v169 offset:6208
	ds_read_b64_tr_b16 v[224:225], v169 offset:7744
	ds_read_b64_tr_b16 v[218:219], v169 offset:9280
	ds_read_b64_tr_b16 v[220:221], v169 offset:10816
	s_waitcnt lgkmcnt(0)
	s_waitcnt vmcnt(4)
	ds_write_b128 v170, v[90:93]
	s_waitcnt vmcnt(3)
	ds_write_b128 v171, v[94:97]
	s_waitcnt vmcnt(1)
	ds_write_b128 v172, v[98:101]
	ds_write_b128 v173, v[102:105] offset:13312
	s_waitcnt vmcnt(0)
	ds_write_b128 v173, v[106:109] offset:13504
	s_waitcnt lgkmcnt(0)
	s_barrier
; DI f32x16 mfma32(bf16x8 a, bf16x8 b, f32x16 c) { return __builtin_amdgcn_mfma_f32_32x32x16_bf16(a, b, c, 0, 0, 0); }
; DI int crow(int reg, int h) { return (reg & 3) + 8 * (reg >> 2) + 4 * h; }
; template <int DQK, int DV, int KW0, int MODE> ...
;     ...
;     {
;       bf16x8 kfa[DQK / 16], kfb[DQK / 16], qv[DQK / 16];
; #pragma unroll
;       for (int kk = 0; kk < DQK / 16; ++kk) {
;         kfa[kk] = *(const bf16x8*)(cur + r * (KS * 2) + kk * 32 + h * 16);
;         kfb[kk] = *(const bf16x8*)(cur + (32 + r) * (KS * 2) + kk * 32 + h * 16);
;         qv[kk] = QLDS ? *(const bf16x8*)(qbase + kk * 1024) : qf[kk];
;       }
; #pragma unroll
;       for (int kk = 0; kk < DQK / 16; ++kk) {
;         S0 = mfma32(kfa[kk], qv[kk], S0);
;         S1 = mfma32(kfb[kk], qv[kk], S1);
;       }
;       __builtin_amdgcn_sched_group_barrier(0x100, (QLDS ? 3 : 2) * (DQK / 16), 0);
;       __builtin_amdgcn_sched_group_barrier(0x008, 2 * (DQK / 16), 0);
;     }
;     if (MODE == 2) {
;       if (it >= 4) {
;         const int w = wlo + it - 4;
;         if (w < 2 || w > 3) {
;           const int kpos0 = (qn - 1) * 128 + 64 * w, qpos = qn * 128 + wid * 32 + r;
; #pragma unroll
;           for (int e = 0; e < 16; ++e) {
;             const int d0 = qpos - (kpos0 + crow(e, h)), d1 = d0 - 32;
;             if (d0 > 128 || d0 < -128) S0[e] = -1e30f;
;             if (d1 > 128 || d1 < -128) S1[e] = -1e30f;
;           }
;         }
;       }
;     }
;     float mx = S0[0];
; #pragma unroll
;     for (int e = 1; e < 16; ++e) mx = fmaxf(mx, S0[e]);
; #pragma unroll
;     for (int e = 0; e < 16; ++e) mx = fmaxf(mx, S1[e]);
;     mx = fmaxf(mx, __shfl_xor(mx, 32));
;     const float mn = fmaxf(m, mx);
;     const bool grow = __builtin_amdgcn_ballot_w64(mx > m) != 0ull;
;     const float alpha = __builtin_amdgcn_exp2f((m - mn) * c);
;     m = mn;
;     const float mc = mn * c;
;     float ps = 0.f;
; #pragma unroll
;     for (int e = 0; e < 16; ++e) { S0[e] = __builtin_amdgcn_exp2f(S0[e] * c - mc); ps += S0[e]; }
; #pragma unroll
;     for (int e = 0; e < 16; ++e) { S1[e] = __builtin_amdgcn_exp2f(S1[e] * c - mc); ps += S1[e]; }
;     if (grow) {
;       l *= alpha;
; #pragma unroll
;       for (int t = 0; t < DV / 32; ++t)
; #pragma unroll
;         for (int e = 0; e < 16; ++e) O[t][e] *= alpha;
;     }
	v_mfma_f32_32x32x16_bf16 v[18:33], v[230:233], v[34:37], v[18:33]
	v_add_u32_e32 v36, s14, v152
	v_ashrrev_i32_e32 v37, 31, v36
	v_mfma_f32_32x32x16_bf16 v[18:33], v[226:229], v[180:183], v[18:33]
	v_mfma_f32_32x32x16_bf16 v[18:33], v[222:225], v[176:179], v[18:33]
	v_mfma_f32_32x32x16_bf16 v[18:33], v[218:221], v[192:195], v[18:33]
	s_and_saveexec_b64 s[16:17], s[40:41]
	s_xor_b64 s[16:17], exec, s[16:17]
	s_movk_i32 s10, 0xff80
	v_mad_i64_i32 v[34:35], s[46:47], v36, s35, v[116:117]
	s_mov_b32 s11, -1
	v_lshl_add_u64 v[34:35], v[34:35], 0, s[10:11]
	s_andn2_saveexec_b64 s[16:17], s[16:17]
	v_lshlrev_b64 v[34:35], 11, v[36:37]
	v_lshl_add_u64 v[34:35], v[142:143], 0, v[34:35]
	s_or_b64 exec, exec, s[16:17]
	global_load_dwordx4 v[90:93], v[34:35], off
	v_add_u32_e32 v36, s14, v153
	v_ashrrev_i32_e32 v37, 31, v36
	s_and_saveexec_b64 s[16:17], s[42:43]
	s_xor_b64 s[16:17], exec, s[16:17]
	s_movk_i32 s10, 0xff80
	v_mad_i64_i32 v[34:35], s[46:47], v36, s35, v[120:121]
	s_mov_b32 s11, -1
	v_lshl_add_u64 v[34:35], v[34:35], 0, s[10:11]
	s_andn2_saveexec_b64 s[16:17], s[16:17]
	v_lshlrev_b64 v[34:35], 11, v[36:37]
	v_lshl_add_u64 v[34:35], v[144:145], 0, v[34:35]
	s_or_b64 exec, exec, s[16:17]
	global_load_dwordx4 v[94:97], v[34:35], off
	v_add_u32_e32 v36, s14, v154
	v_ashrrev_i32_e32 v37, 31, v36
	s_and_saveexec_b64 s[16:17], s[44:45]
	s_xor_b64 s[16:17], exec, s[16:17]
	s_movk_i32 s10, 0xff80
	v_mad_i64_i32 v[34:35], s[46:47], v36, s35, v[126:127]
	s_mov_b32 s11, -1
	v_lshl_add_u64 v[34:35], v[34:35], 0, s[10:11]
	s_andn2_saveexec_b64 s[16:17], s[16:17]
	v_lshlrev_b64 v[34:35], 11, v[36:37]
	v_lshl_add_u64 v[34:35], v[146:147], 0, v[34:35]
	s_or_b64 exec, exec, s[16:17]
	s_ashr_i32 s15, s14, 31
	s_lshl_b64 s[14:15], s[14:15], 11
	s_add_u32 s14, s12, s14
	s_addc_u32 s15, s13, s15
	global_load_dwordx4 v[98:101], v[34:35], off
	v_lshl_add_u64 v[34:35], s[14:15], 0, v[138:139]
	global_load_dwordx4 v[102:105], v[34:35], off offset:128
	v_lshl_add_u64 v[34:35], s[14:15], 0, v[140:141]
	global_load_dwordx4 v[106:109], v[34:35], off offset:128
	v_add_f32_e32 v36, 0, v50
	v_add_f32_e32 v36, v51, v36
	v_add_f32_e32 v36, v52, v36
	v_add_f32_e32 v36, v53, v36
	v_add_f32_e32 v36, v54, v36
	v_add_f32_e32 v36, v55, v36
	v_add_f32_e32 v36, v56, v36
	v_add_f32_e32 v36, v57, v36
	v_add_f32_e32 v36, v58, v36
	v_add_f32_e32 v36, v59, v36
	v_add_f32_e32 v36, v60, v36
	v_add_f32_e32 v36, v61, v36
	v_add_f32_e32 v36, v62, v36
	v_add_f32_e32 v36, v63, v36
	v_add_f32_e32 v36, v64, v36
	v_add_f32_e32 v36, v65, v36
	v_add_f32_e32 v36, v149, v36
	v_add_f32_e32 v36, v150, v36
	v_add_f32_e32 v36, v151, v36
	v_add_f32_e32 v36, v175, v36
	v_add_f32_e32 v36, v38, v36
	v_add_f32_e32 v36, v39, v36
	v_add_f32_e32 v36, v40, v36
	v_add_f32_e32 v36, v41, v36
	v_add_f32_e32 v36, v42, v36
	v_add_f32_e32 v36, v43, v36
	v_add_f32_e32 v36, v44, v36
	v_add_f32_e32 v36, v45, v36
	v_add_f32_e32 v36, v46, v36
	v_add_f32_e32 v36, v47, v36
	v_add_f32_e32 v36, v48, v36
	v_add_f32_e32 v36, v49, v36
	v_add_f32_e32 v113, v36, v113
	ds_read_b128 v[38:41], v174
	ds_read_b128 v[42:45], v174 offset:32
	ds_read_b128 v[34:37], v174 offset:6656
	ds_read_b128 v[176:179], v174 offset:6688
	ds_read_b128 v[46:49], v174 offset:64
	ds_read_b128 v[180:183], v174 offset:6720
	ds_read_b128 v[192:195], v174 offset:96
	ds_read_b128 v[218:221], v174 offset:6752
	ds_read_b128 v[222:225], v174 offset:128
	ds_read_b128 v[226:229], v174 offset:6784
	ds_read_b128 v[230:233], v174 offset:160
	ds_read_b128 v[234:237], v174 offset:6816
	s_waitcnt lgkmcnt(11)
	v_mfma_f32_32x32x16_bf16 v[50:65], v[38:41], v[66:69], 0
	s_waitcnt lgkmcnt(10)
	v_mfma_f32_32x32x16_bf16 v[50:65], v[42:45], v[70:73], v[50:65]
	s_waitcnt lgkmcnt(7)
	v_mfma_f32_32x32x16_bf16 v[50:65], v[46:49], v[74:77], v[50:65]
	v_mfma_f32_32x32x16_bf16 v[34:49], v[34:37], v[66:69], 0
	v_mfma_f32_32x32x16_bf16 v[34:49], v[176:179], v[70:73], v[34:49]
	s_waitcnt lgkmcnt(5)
	v_mfma_f32_32x32x16_bf16 v[50:65], v[192:195], v[78:81], v[50:65]
	v_mfma_f32_32x32x16_bf16 v[34:49], v[180:183], v[74:77], v[34:49]
	s_waitcnt lgkmcnt(3)
	v_mfma_f32_32x32x16_bf16 v[50:65], v[222:225], v[82:85], v[50:65]
	v_mfma_f32_32x32x16_bf16 v[34:49], v[218:221], v[78:81], v[34:49]
	s_waitcnt lgkmcnt(1)
	v_mfma_f32_32x32x16_bf16 v[50:65], v[230:233], v[86:89], v[50:65]
	v_mfma_f32_32x32x16_bf16 v[34:49], v[226:229], v[82:85], v[34:49]
	s_nop 10
	v_max_f32_e32 v149, v51, v51
	v_max_f32_e32 v150, v50, v50
	v_max_f32_e32 v149, v150, v149
	v_max3_f32 v149, v149, v52, v53
	v_max3_f32 v149, v149, v54, v55
	v_max3_f32 v149, v149, v56, v57
	v_max3_f32 v149, v149, v58, v59
	s_waitcnt lgkmcnt(0)
	v_mfma_f32_32x32x16_bf16 v[34:49], v[234:237], v[86:89], v[34:49]
	v_max3_f32 v149, v149, v60, v61
	v_max3_f32 v149, v149, v62, v63
	v_max3_f32 v149, v149, v64, v65
	s_nop 8
	v_max3_f32 v149, v149, v34, v35
	v_max3_f32 v149, v149, v36, v37
	v_max3_f32 v149, v149, v38, v39
	v_max3_f32 v149, v149, v40, v41
	v_max3_f32 v149, v149, v42, v43
	v_max3_f32 v149, v149, v44, v45
	v_max3_f32 v149, v149, v46, v47
	v_max3_f32 v149, v149, v48, v49
	v_mov_b32_e32 v150, v149
	s_nop 1
	v_permlane32_swap_b32_e32 v150, v149
	s_waitcnt lgkmcnt(0)
	v_max_f32_e32 v150, v149, v150
	v_max_f32_e32 v149, v148, v148
	v_max_f32_e32 v149, v149, v150
	v_cmp_gt_f32_e32 vcc, v150, v148
	s_cbranch_vccz .LBB0_119
	v_sub_f32_e32 v148, v148, v149
	v_mul_f32_e32 v148, 0x3e16c740, v148
	v_exp_f32_e32 v148, v148
	s_nop 0
	v_pk_mul_f32 v[32:33], v[32:33], v[148:149] op_sel_hi:[1,0]
	v_pk_mul_f32 v[30:31], v[30:31], v[148:149] op_sel_hi:[1,0]
	v_pk_mul_f32 v[28:29], v[28:29], v[148:149] op_sel_hi:[1,0]
	v_pk_mul_f32 v[26:27], v[26:27], v[148:149] op_sel_hi:[1,0]
	v_pk_mul_f32 v[24:25], v[24:25], v[148:149] op_sel_hi:[1,0]
	v_pk_mul_f32 v[22:23], v[22:23], v[148:149] op_sel_hi:[1,0]
	v_pk_mul_f32 v[20:21], v[20:21], v[148:149] op_sel_hi:[1,0]
	v_pk_mul_f32 v[18:19], v[18:19], v[148:149] op_sel_hi:[1,0]
	v_pk_mul_f32 v[16:17], v[16:17], v[148:149] op_sel_hi:[1,0]
	v_pk_mul_f32 v[14:15], v[14:15], v[148:149] op_sel_hi:[1,0]
	v_pk_mul_f32 v[12:13], v[12:13], v[148:149] op_sel_hi:[1,0]
	v_pk_mul_f32 v[10:11], v[10:11], v[148:149] op_sel_hi:[1,0]
	v_pk_mul_f32 v[8:9], v[8:9], v[148:149] op_sel_hi:[1,0]
	v_pk_mul_f32 v[6:7], v[6:7], v[148:149] op_sel_hi:[1,0]
	v_pk_mul_f32 v[4:5], v[4:5], v[148:149] op_sel_hi:[1,0]
	v_pk_mul_f32 v[2:3], v[2:3], v[148:149] op_sel_hi:[1,0]
	v_mul_f32_e32 v113, v113, v148

; DI f32x16 mfma32(bf16x8 a, bf16x8 b, f32x16 c) { return __builtin_amdgcn_mfma_f32_32x32x16_bf16(a, b, c, 0, 0, 0); }
; DI int crow(int reg, int h) { return (reg & 3) + 8 * (reg >> 2) + 4 * h; }
; template <int DQK, int DV, int KW0, int MODE> ...
;     ...
;       for (int kk = 0; kk < DQK / 16; ++kk) {
;         kfa[kk] = *(const bf16x8*)(cur + r * (KS * 2) + kk * 32 + h * 16);
;         kfb[kk] = *(const bf16x8*)(cur + (32 + r) * (KS * 2) + kk * 32 + h * 16);
;         qv[kk] = QLDS ? *(const bf16x8*)(qbase + kk * 1024) : qf[kk];
;       }
; #pragma unroll
;       for (int kk = 0; kk < DQK / 16; ++kk) {
;         S0 = mfma32(kfa[kk], qv[kk], S0);
;         S1 = mfma32(kfb[kk], qv[kk], S1);
;       }
;       __builtin_amdgcn_sched_group_barrier(0x100, (QLDS ? 3 : 2) * (DQK / 16), 0);
;       __builtin_amdgcn_sched_group_barrier(0x008, 2 * (DQK / 16), 0);
;     }
;     if (MODE == 2) {
;       if (it >= 4) {
;         const int w = wlo + it - 4;
;         if (w < 2 || w > 3) {
;           const int kpos0 = (qn - 1) * 128 + 64 * w, qpos = qn * 128 + wid * 32 + r;
; #pragma unroll
;           for (int e = 0; e < 16; ++e) {
;             const int d0 = qpos - (kpos0 + crow(e, h)), d1 = d0 - 32;
;             if (d0 > 128 || d0 < -128) S0[e] = -1e30f;
;             if (d1 > 128 || d1 < -128) S1[e] = -1e30f;
;           }
;         }
;       }
;     }
;     float mx = S0[0];
; #pragma unroll
;     for (int e = 1; e < 16; ++e) mx = fmaxf(mx, S0[e]);
; #pragma unroll
;     for (int e = 0; e < 16; ++e) mx = fmaxf(mx, S1[e]);
;     mx = fmaxf(mx, __shfl_xor(mx, 32));
;     const float mn = fmaxf(m, mx);
;     const bool grow = __builtin_amdgcn_ballot_w64(mx > m) != 0ull;
;     const float alpha = __builtin_amdgcn_exp2f((m - mn) * c);
;     m = mn;
;     const float mc = mn * c;
;     float ps = 0.f;
; #pragma unroll
;     for (int e = 0; e < 16; ++e) { S0[e] = __builtin_amdgcn_exp2f(S0[e] * c - mc); ps += S0[e]; }
; #pragma unroll
;     for (int e = 0; e < 16; ++e) { S1[e] = __builtin_amdgcn_exp2f(S1[e] * c - mc); ps += S1[e]; }
;     if (grow) {
;       l *= alpha;
; #pragma unroll
;       for (int t = 0; t < DV / 32; ++t)
; #pragma unroll
;         for (int e = 0; e < 16; ++e) O[t][e] *= alpha;
.LBB0_134:
	s_bitcmp1_b32 s46, 0
	s_cselect_b32 s10, 0x6400, 0
	s_add_i32 s15, s10, 16
	v_add3_u32 v50, s15, v164, v165
	ds_read_b128 v[38:41], v50
	ds_read_b128 v[42:45], v50 offset:32
	ds_read_b128 v[34:37], v50 offset:6656
	ds_read_b128 v[176:179], v50 offset:6688
	ds_read_b128 v[46:49], v50 offset:64
	ds_read_b128 v[180:183], v50 offset:6720
	ds_read_b128 v[192:195], v50 offset:96
	ds_read_b128 v[218:221], v50 offset:6752
	ds_read_b128 v[222:225], v50 offset:128
	ds_read_b128 v[226:229], v50 offset:6784
	ds_read_b128 v[230:233], v50 offset:160
	ds_read_b128 v[234:237], v50 offset:6816
	s_setprio 1
	s_waitcnt lgkmcnt(11)
	v_mfma_f32_32x32x16_bf16 v[50:65], v[38:41], v[66:69], 0
	s_waitcnt lgkmcnt(10)
	v_mfma_f32_32x32x16_bf16 v[50:65], v[42:45], v[70:73], v[50:65]
	s_waitcnt lgkmcnt(7)
	v_mfma_f32_32x32x16_bf16 v[50:65], v[46:49], v[74:77], v[50:65]
	v_mfma_f32_32x32x16_bf16 v[34:49], v[34:37], v[66:69], 0
	v_mfma_f32_32x32x16_bf16 v[34:49], v[176:179], v[70:73], v[34:49]
	s_waitcnt lgkmcnt(5)
	v_mfma_f32_32x32x16_bf16 v[50:65], v[192:195], v[78:81], v[50:65]
	v_mfma_f32_32x32x16_bf16 v[34:49], v[180:183], v[74:77], v[34:49]
	s_waitcnt lgkmcnt(3)
	v_mfma_f32_32x32x16_bf16 v[50:65], v[222:225], v[82:85], v[50:65]
	v_mfma_f32_32x32x16_bf16 v[34:49], v[218:221], v[78:81], v[34:49]
	s_waitcnt lgkmcnt(1)
	v_mfma_f32_32x32x16_bf16 v[50:65], v[230:233], v[86:89], v[50:65]
	v_mfma_f32_32x32x16_bf16 v[34:49], v[226:229], v[82:85], v[34:49]
	s_nop 10
	v_max_f32_e32 v148, v51, v51
	v_max_f32_e32 v150, v50, v50
	v_max_f32_e32 v148, v150, v148
	v_max3_f32 v148, v148, v52, v53
	v_max3_f32 v148, v148, v54, v55
	v_max3_f32 v148, v148, v56, v57
	v_max3_f32 v148, v148, v58, v59
	s_waitcnt lgkmcnt(0)
	v_mfma_f32_32x32x16_bf16 v[34:49], v[234:237], v[86:89], v[34:49]
	s_setprio 0
	v_max3_f32 v148, v148, v60, v61
	v_max3_f32 v148, v148, v62, v63
	v_max3_f32 v148, v148, v64, v65
	s_nop 8
	v_max3_f32 v148, v148, v34, v35
	v_max3_f32 v148, v148, v36, v37
	v_max3_f32 v148, v148, v38, v39
	v_max3_f32 v148, v148, v40, v41
	v_max3_f32 v148, v148, v42, v43
	v_max3_f32 v148, v148, v44, v45
	v_max3_f32 v148, v148, v46, v47
	v_max3_f32 v148, v148, v48, v49
	v_mov_b32_e32 v150, v148
	s_nop 1
	v_permlane32_swap_b32_e32 v150, v148
	s_waitcnt lgkmcnt(0)
	v_max_f32_e32 v148, v148, v150
	v_max_f32_e32 v150, v149, v149
	v_max_f32_e32 v151, v150, v148
	v_cmp_gt_f32_e32 vcc, v148, v149
	s_cbranch_vccz .LBB0_136
	v_sub_f32_e32 v148, v149, v151
	v_mul_f32_e32 v148, 0x3e16c740, v148
	v_exp_f32_e32 v148, v148
	s_nop 0
	v_pk_mul_f32 v[32:33], v[32:33], v[148:149] op_sel_hi:[1,0]
	v_pk_mul_f32 v[30:31], v[30:31], v[148:149] op_sel_hi:[1,0]
	v_pk_mul_f32 v[28:29], v[28:29], v[148:149] op_sel_hi:[1,0]
	v_pk_mul_f32 v[26:27], v[26:27], v[148:149] op_sel_hi:[1,0]
	v_pk_mul_f32 v[24:25], v[24:25], v[148:149] op_sel_hi:[1,0]
	v_pk_mul_f32 v[22:23], v[22:23], v[148:149] op_sel_hi:[1,0]
	v_pk_mul_f32 v[20:21], v[20:21], v[148:149] op_sel_hi:[1,0]
	v_pk_mul_f32 v[18:19], v[18:19], v[148:149] op_sel_hi:[1,0]
	v_pk_mul_f32 v[16:17], v[16:17], v[148:149] op_sel_hi:[1,0]
	v_pk_mul_f32 v[14:15], v[14:15], v[148:149] op_sel_hi:[1,0]
	v_pk_mul_f32 v[12:13], v[12:13], v[148:149] op_sel_hi:[1,0]
	v_pk_mul_f32 v[10:11], v[10:11], v[148:149] op_sel_hi:[1,0]
	v_pk_mul_f32 v[8:9], v[8:9], v[148:149] op_sel_hi:[1,0]
	v_pk_mul_f32 v[6:7], v[6:7], v[148:149] op_sel_hi:[1,0]
	v_pk_mul_f32 v[4:5], v[4:5], v[148:149] op_sel_hi:[1,0]
	v_pk_mul_f32 v[2:3], v[2:3], v[148:149] op_sel_hi:[1,0]
	v_mul_f32_e32 v113, v113, v148
